# GEMM K loops: global loads use scalar-base + per-lane 32-bit offset addressing (no per-load 64-bit VALU address adds)
# baseline (speedup 1.0000x reference)
.LBB0_372:
	s_mul_hi_i32 s0, s43, 0x55555556
	s_lshr_b32 s1, s0, 31
	s_add_i32 s0, s0, s1
	s_lshl_b32 s12, s0, 7
	s_mul_i32 s0, s0, 3
	s_sub_i32 s0, s43, s0
	v_mov_b32_e32 v1, v0
	s_lshl_b32 s44, s0, 3
	s_add_i32 s44, s44, s41
	s_waitcnt vmcnt(4)
	v_ashrrev_i32_e32 v8, 3, v1
	v_and_b32_e32 v9, 7, v1
	v_add_u32_e32 v4, s12, v8
	v_mov_b64_e32 v[2:3], s[66:67]
	s_lshl_b32 s13, s44, 7
	v_mad_i64_i32 v[2:3], s[0:1], v4, s58, v[2:3]
	v_lshlrev_b32_e32 v106, 4, v9
	v_lshl_add_u64 v[98:99], v[2:3], 0, v[106:107]
	v_add_u32_e32 v4, s13, v8
	v_mov_b64_e32 v[2:3], s[2:3]
	v_mad_i64_i32 v[2:3], s[0:1], v4, s58, v[2:3]
	s_mov_b32 s0, 0x11000
	s_nop 0
	v_add_co_u32_e32 v4, vcc, s0, v98
	s_mov_b32 s1, 0x22000
	s_nop 0
	v_addc_co_u32_e32 v5, vcc, 0, v99, vcc
	v_add_co_u32_e32 v6, vcc, s1, v98
	s_mov_b32 s4, 0x33000
	s_nop 0
	v_addc_co_u32_e32 v7, vcc, 0, v99, vcc
	v_add_co_u32_e32 v4, vcc, s4, v98
	v_lshl_add_u64 v[100:101], v[2:3], 0, v[106:107]
	s_nop 0
	v_addc_co_u32_e32 v5, vcc, 0, v99, vcc
	v_add_co_u32_e32 v2, vcc, s0, v100
	s_nop 0
	v_addc_co_u32_e32 v3, vcc, 0, v101, vcc
	v_add_co_u32_e32 v4, vcc, s1, v100
	s_nop 0
	v_addc_co_u32_e32 v5, vcc, 0, v101, vcc
	v_add_co_u32_e32 v2, vcc, s4, v100
	v_lshrrev_b32_e32 v4, 5, v1
	s_nop 0
	v_addc_co_u32_e32 v3, vcc, 0, v101, vcc
	v_ashrrev_i32_e32 v3, 4, v1
	s_waitcnt vmcnt(11)
	v_xor_b32_e32 v10, v3, v1
	v_and_b32_e32 v3, 1, v3
	v_and_b32_e32 v4, 6, v4
	v_lshrrev_b32_e32 v2, 4, v1
	v_bfe_u32 v102, v1, 4, 2
	v_bfe_u32 v5, v1, 1, 3
	v_bitop3_b32 v3, v3, v9, v4 bitop3:0x36
	v_ashrrev_i32_e32 v103, 7, v1
	v_lshlrev_b32_e32 v105, 7, v8
	v_bitop3_b32 v2, v2, v5, 3 bitop3:0x6c
	v_bitop3_b32 v5, v102, v5, 4 bitop3:0x36
	v_lshlrev_b32_e32 v4, 4, v10
	s_movk_i32 s0, 0x70
	v_lshlrev_b32_e32 v111, 4, v3
	v_and_b32_e32 v104, 15, v1
	v_lshlrev_b32_e32 v6, 1, v1
	v_and_b32_e32 v7, 0x43, v1
	v_lshlrev_b32_e32 v8, 13, v103
	v_lshlrev_b32_e32 v106, 4, v2
	v_lshlrev_b32_e32 v109, 4, v5
	v_and_or_b32 v110, v4, s0, v105
	v_or_b32_e32 v2, v105, v111
	v_lshlrev_b32_e32 v11, 7, v104
	v_and_or_b32 v6, v6, 24, v7
	v_or_b32_e32 v3, v106, v8
	v_or_b32_e32 v4, v109, v8
	v_lshlrev_b32_e32 v108, 7, v6
	s_mov_b64 s[0:1], 0
	v_lshrrev_b32_e32 v220, 3, v0
	v_and_b32_e32 v221, 7, v0
	s_movk_i32 vcc_lo, 0x880
	v_mul_lo_u32 v220, v220, vcc_lo
	v_lshl_add_u32 v216, v221, 4, v220
	v_add_u32_e32 v217, 0x11000, v216
	v_add_u32_e32 v218, 0x22000, v216
	v_add_u32_e32 v219, 0x33000, v216
	s_mul_i32 s0, s12, vcc_lo
	s_add_u32 s0, s66, s0
	s_addc_u32 s1, s67, 0
	s_mul_i32 s6, s13, vcc_lo
	s_add_u32 s6, s2, s6
	s_addc_u32 s7, s3, 0
	global_load_dwordx4 v[224:227], v216, s[0:1] offset:128
	global_load_dwordx4 v[228:231], v217, s[0:1] offset:128
	global_load_dwordx4 v[232:235], v218, s[0:1] offset:128
	global_load_dwordx4 v[236:239], v219, s[0:1] offset:128
	global_load_dwordx4 v[240:243], v216, s[6:7] offset:128
	global_load_dwordx4 v[244:247], v217, s[6:7] offset:128
	global_load_dwordx4 v[248:251], v218, s[6:7] offset:128
	global_load_dwordx4 v[252:255], v219, s[6:7] offset:128
	v_add_u32_e32 v112, v3, v11
	v_add_u32_e32 v113, v4, v11
	s_waitcnt vmcnt(15)
	ds_write_b128 v110, v[164:167]
	s_waitcnt vmcnt(14)
	ds_write_b128 v110, v[168:171] offset:4096
	s_waitcnt vmcnt(13)
	ds_write_b128 v110, v[172:175] offset:8192
	s_waitcnt vmcnt(12)
	ds_write_b128 v110, v[176:179] offset:12288
	s_waitcnt vmcnt(11)
	ds_write_b128 v2, v[180:183] offset:16384
	s_waitcnt vmcnt(10)
	ds_write_b128 v2, v[184:187] offset:20480
	s_waitcnt vmcnt(9)
	ds_write_b128 v2, v[192:195] offset:24576
	s_waitcnt vmcnt(8)
	ds_write_b128 v2, v[196:199] offset:28672
	v_mov_b32_e32 v2, 0
	v_mov_b32_e32 v3, v2
	v_mov_b32_e32 v4, v2
	v_mov_b32_e32 v5, v2
	v_mov_b32_e32 v6, v2
	v_mov_b32_e32 v7, v2
	v_mov_b32_e32 v8, v2
	v_mov_b32_e32 v9, v2
	v_mov_b32_e32 v10, v2
	v_mov_b32_e32 v11, v2
	v_mov_b32_e32 v12, v2
	v_mov_b32_e32 v13, v2
	v_mov_b32_e32 v14, v2
	v_mov_b32_e32 v15, v2
	v_mov_b32_e32 v16, v2
	v_mov_b32_e32 v17, v2
	v_mov_b32_e32 v18, v2
	v_mov_b32_e32 v19, v2
	v_mov_b32_e32 v20, v2
	v_mov_b32_e32 v21, v2
	v_mov_b32_e32 v22, v2
	v_mov_b32_e32 v23, v2
	v_mov_b32_e32 v24, v2
	v_mov_b32_e32 v25, v2
	v_mov_b32_e32 v26, v2
	v_mov_b32_e32 v27, v2
	v_mov_b32_e32 v28, v2
	v_mov_b32_e32 v29, v2
	v_mov_b32_e32 v30, v2
	v_mov_b32_e32 v31, v2
	v_mov_b32_e32 v32, v2
	v_mov_b32_e32 v33, v2
	v_mov_b32_e32 v34, v2
	v_mov_b32_e32 v35, v2
	v_mov_b32_e32 v36, v2
	v_mov_b32_e32 v37, v2
	v_mov_b32_e32 v38, v2
	v_mov_b32_e32 v39, v2
	v_mov_b32_e32 v40, v2
	v_mov_b32_e32 v41, v2
	v_mov_b32_e32 v42, v2
	v_mov_b32_e32 v43, v2
	v_mov_b32_e32 v44, v2
	v_mov_b32_e32 v45, v2
	v_mov_b32_e32 v46, v2
	v_mov_b32_e32 v47, v2
	v_mov_b32_e32 v48, v2
	v_mov_b32_e32 v49, v2
	v_mov_b32_e32 v50, v2
	v_mov_b32_e32 v51, v2
	v_mov_b32_e32 v52, v2
	v_mov_b32_e32 v53, v2
	v_mov_b32_e32 v54, v2
	v_mov_b32_e32 v55, v2
	v_mov_b32_e32 v56, v2
	v_mov_b32_e32 v57, v2
	v_mov_b32_e32 v58, v2
	v_mov_b32_e32 v59, v2
	v_mov_b32_e32 v60, v2
	v_mov_b32_e32 v61, v2
	v_mov_b32_e32 v66, v2
	v_mov_b32_e32 v67, v2
	v_mov_b32_e32 v68, v2
	v_mov_b32_e32 v69, v2
	v_add_u32_e32 v188, v106, v108
	v_add_u32_e32 v189, v109, v108
	v_add_u32_e32 v190, v105, v111
	s_waitcnt lgkmcnt(0)
	s_barrier
	s_branch .LBB0_374
.LBB0_374:
	s_movk_i32 vcc_lo, 7
.Lgq_c:
	ds_read_b128 v[114:117], v188 offset:16384
	ds_read_b128 v[118:121], v188 offset:16896
	ds_read_b128 v[156:159], v188 offset:20480
	ds_read_b128 v[160:163], v188 offset:20992
	ds_read_b128 v[122:125], v112
	ds_read_b128 v[126:129], v112 offset:2048
	global_load_dwordx4 v[62:65], v216, s[0:1] offset:256
	global_load_dwordx4 v[70:73], v217, s[0:1] offset:256
	s_waitcnt lgkmcnt(1)
	v_mfma_f32_16x16x32_bf16 v[66:69], v[114:117], v[122:125], v[66:69]
	v_mfma_f32_16x16x32_bf16 v[58:61], v[118:121], v[122:125], v[58:61]
	global_load_dwordx4 v[74:77], v218, s[0:1] offset:256
	v_mfma_f32_16x16x32_bf16 v[54:57], v[156:159], v[122:125], v[54:57]
	v_mfma_f32_16x16x32_bf16 v[50:53], v[160:163], v[122:125], v[50:53]
	s_waitcnt lgkmcnt(0)
	v_mfma_f32_16x16x32_bf16 v[46:49], v[114:117], v[126:129], v[46:49]
	ds_read_b128 v[180:183], v112 offset:4096
	ds_read_b128 v[184:187], v112 offset:6144
	v_mfma_f32_16x16x32_bf16 v[42:45], v[118:121], v[126:129], v[42:45]
	v_mfma_f32_16x16x32_bf16 v[38:41], v[156:159], v[126:129], v[38:41]
	global_load_dwordx4 v[78:81], v219, s[0:1] offset:256
	v_mfma_f32_16x16x32_bf16 v[34:37], v[160:163], v[126:129], v[34:37]
	s_waitcnt lgkmcnt(1)
	v_mfma_f32_16x16x32_bf16 v[30:33], v[114:117], v[180:183], v[30:33]
	ds_read_b128 v[164:167], v189 offset:16384
	ds_read_b128 v[168:171], v189 offset:16896
	v_mfma_f32_16x16x32_bf16 v[26:29], v[118:121], v[180:183], v[26:29]
	global_load_dwordx4 v[82:85], v216, s[6:7] offset:256
	v_mfma_f32_16x16x32_bf16 v[22:25], v[156:159], v[180:183], v[22:25]
	ds_read_b128 v[172:175], v189 offset:20480
	ds_read_b128 v[176:179], v189 offset:20992
	v_mfma_f32_16x16x32_bf16 v[18:21], v[160:163], v[180:183], v[18:21]
	s_waitcnt lgkmcnt(4)
	v_mfma_f32_16x16x32_bf16 v[14:17], v[114:117], v[184:187], v[14:17]
	ds_read_b128 v[122:125], v113
	ds_read_b128 v[126:129], v113 offset:2048
	v_mfma_f32_16x16x32_bf16 v[10:13], v[118:121], v[184:187], v[10:13]
	v_mfma_f32_16x16x32_bf16 v[6:9], v[156:159], v[184:187], v[6:9]
	global_load_dwordx4 v[86:89], v217, s[6:7] offset:256
	v_mfma_f32_16x16x32_bf16 v[2:5], v[160:163], v[184:187], v[2:5]
	s_waitcnt lgkmcnt(1)
	v_mfma_f32_16x16x32_bf16 v[66:69], v[164:167], v[122:125], v[66:69]
	v_mfma_f32_16x16x32_bf16 v[58:61], v[168:171], v[122:125], v[58:61]
	global_load_dwordx4 v[90:93], v218, s[6:7] offset:256
	v_mfma_f32_16x16x32_bf16 v[54:57], v[172:175], v[122:125], v[54:57]
	v_mfma_f32_16x16x32_bf16 v[50:53], v[176:179], v[122:125], v[50:53]
	s_waitcnt lgkmcnt(0)
	v_mfma_f32_16x16x32_bf16 v[46:49], v[164:167], v[126:129], v[46:49]
	ds_read_b128 v[180:183], v113 offset:4096
	ds_read_b128 v[184:187], v113 offset:6144
	v_mfma_f32_16x16x32_bf16 v[42:45], v[168:171], v[126:129], v[42:45]
	v_mfma_f32_16x16x32_bf16 v[38:41], v[172:175], v[126:129], v[38:41]
	global_load_dwordx4 v[94:97], v219, s[6:7] offset:256
	v_mfma_f32_16x16x32_bf16 v[34:37], v[176:179], v[126:129], v[34:37]
	s_waitcnt lgkmcnt(1)
	v_mfma_f32_16x16x32_bf16 v[30:33], v[164:167], v[180:183], v[30:33]
	s_waitcnt vmcnt(15)
	ds_write_b128 v110, v[224:227] offset:32768
	v_mfma_f32_16x16x32_bf16 v[26:29], v[168:171], v[180:183], v[26:29]
	s_waitcnt vmcnt(14)
	ds_write_b128 v110, v[228:231] offset:36864
	v_mfma_f32_16x16x32_bf16 v[22:25], v[172:175], v[180:183], v[22:25]
	s_waitcnt vmcnt(13)
	ds_write_b128 v110, v[232:235] offset:40960
	v_mfma_f32_16x16x32_bf16 v[18:21], v[176:179], v[180:183], v[18:21]
	s_waitcnt vmcnt(12)
	ds_write_b128 v110, v[236:239] offset:45056
	s_waitcnt lgkmcnt(4)
	v_mfma_f32_16x16x32_bf16 v[14:17], v[164:167], v[184:187], v[14:17]
	s_waitcnt vmcnt(11)
	ds_write_b128 v190, v[240:243] offset:49168
	v_mfma_f32_16x16x32_bf16 v[10:13], v[168:171], v[184:187], v[10:13]
	s_waitcnt vmcnt(10)
	ds_write_b128 v190, v[244:247] offset:53264
	v_mfma_f32_16x16x32_bf16 v[6:9], v[172:175], v[184:187], v[6:9]
	s_waitcnt vmcnt(9)
	ds_write_b128 v190, v[248:251] offset:57360
	v_mfma_f32_16x16x32_bf16 v[2:5], v[176:179], v[184:187], v[2:5]
	s_waitcnt vmcnt(8)
	ds_write_b128 v190, v[252:255] offset:61456
	s_waitcnt lgkmcnt(0)
	s_barrier
	s_add_u32 s0, s0, 0x80
	s_addc_u32 s1, s1, 0
	s_add_u32 s6, s6, 0x80
	s_addc_u32 s7, s7, 0
	ds_read_b128 v[114:117], v188 offset:49168
	ds_read_b128 v[118:121], v188 offset:49680
	ds_read_b128 v[156:159], v188 offset:53264
	ds_read_b128 v[160:163], v188 offset:53776
	ds_read_b128 v[122:125], v112 offset:32768
	ds_read_b128 v[126:129], v112 offset:34816
	global_load_dwordx4 v[224:227], v216, s[0:1] offset:256
	global_load_dwordx4 v[228:231], v217, s[0:1] offset:256
	s_waitcnt lgkmcnt(1)
	v_mfma_f32_16x16x32_bf16 v[66:69], v[114:117], v[122:125], v[66:69]
	v_mfma_f32_16x16x32_bf16 v[58:61], v[118:121], v[122:125], v[58:61]
	global_load_dwordx4 v[232:235], v218, s[0:1] offset:256
	v_mfma_f32_16x16x32_bf16 v[54:57], v[156:159], v[122:125], v[54:57]
	v_mfma_f32_16x16x32_bf16 v[50:53], v[160:163], v[122:125], v[50:53]
	s_waitcnt lgkmcnt(0)
	v_mfma_f32_16x16x32_bf16 v[46:49], v[114:117], v[126:129], v[46:49]
	ds_read_b128 v[180:183], v112 offset:36864
	ds_read_b128 v[184:187], v112 offset:38912
	v_mfma_f32_16x16x32_bf16 v[42:45], v[118:121], v[126:129], v[42:45]
	v_mfma_f32_16x16x32_bf16 v[38:41], v[156:159], v[126:129], v[38:41]
	global_load_dwordx4 v[236:239], v219, s[0:1] offset:256
	v_mfma_f32_16x16x32_bf16 v[34:37], v[160:163], v[126:129], v[34:37]
	s_waitcnt lgkmcnt(1)
	v_mfma_f32_16x16x32_bf16 v[30:33], v[114:117], v[180:183], v[30:33]
	ds_read_b128 v[164:167], v189 offset:49168
	ds_read_b128 v[168:171], v189 offset:49680
	v_mfma_f32_16x16x32_bf16 v[26:29], v[118:121], v[180:183], v[26:29]
	global_load_dwordx4 v[240:243], v216, s[6:7] offset:256
	v_mfma_f32_16x16x32_bf16 v[22:25], v[156:159], v[180:183], v[22:25]
	ds_read_b128 v[172:175], v189 offset:53264
	ds_read_b128 v[176:179], v189 offset:53776
	v_mfma_f32_16x16x32_bf16 v[18:21], v[160:163], v[180:183], v[18:21]
	s_waitcnt lgkmcnt(4)
	v_mfma_f32_16x16x32_bf16 v[14:17], v[114:117], v[184:187], v[14:17]
	ds_read_b128 v[122:125], v113 offset:32768
	ds_read_b128 v[126:129], v113 offset:34816
	v_mfma_f32_16x16x32_bf16 v[10:13], v[118:121], v[184:187], v[10:13]
	v_mfma_f32_16x16x32_bf16 v[6:9], v[156:159], v[184:187], v[6:9]
	global_load_dwordx4 v[244:247], v217, s[6:7] offset:256
	v_mfma_f32_16x16x32_bf16 v[2:5], v[160:163], v[184:187], v[2:5]
	s_waitcnt lgkmcnt(1)
	v_mfma_f32_16x16x32_bf16 v[66:69], v[164:167], v[122:125], v[66:69]
	v_mfma_f32_16x16x32_bf16 v[58:61], v[168:171], v[122:125], v[58:61]
	global_load_dwordx4 v[248:251], v218, s[6:7] offset:256
	v_mfma_f32_16x16x32_bf16 v[54:57], v[172:175], v[122:125], v[54:57]
	v_mfma_f32_16x16x32_bf16 v[50:53], v[176:179], v[122:125], v[50:53]
	s_waitcnt lgkmcnt(0)
	v_mfma_f32_16x16x32_bf16 v[46:49], v[164:167], v[126:129], v[46:49]
	ds_read_b128 v[180:183], v113 offset:36864
	ds_read_b128 v[184:187], v113 offset:38912
	v_mfma_f32_16x16x32_bf16 v[42:45], v[168:171], v[126:129], v[42:45]
	v_mfma_f32_16x16x32_bf16 v[38:41], v[172:175], v[126:129], v[38:41]
	global_load_dwordx4 v[252:255], v219, s[6:7] offset:256
	v_mfma_f32_16x16x32_bf16 v[34:37], v[176:179], v[126:129], v[34:37]
	s_waitcnt lgkmcnt(1)
	v_mfma_f32_16x16x32_bf16 v[30:33], v[164:167], v[180:183], v[30:33]
	s_waitcnt vmcnt(15)
	ds_write_b128 v110, v[62:65]
	v_mfma_f32_16x16x32_bf16 v[26:29], v[168:171], v[180:183], v[26:29]
	s_waitcnt vmcnt(14)
	ds_write_b128 v110, v[70:73] offset:4096
	v_mfma_f32_16x16x32_bf16 v[22:25], v[172:175], v[180:183], v[22:25]
	s_waitcnt vmcnt(13)
	ds_write_b128 v110, v[74:77] offset:8192
	v_mfma_f32_16x16x32_bf16 v[18:21], v[176:179], v[180:183], v[18:21]
	s_waitcnt vmcnt(12)
	ds_write_b128 v110, v[78:81] offset:12288
	s_waitcnt lgkmcnt(4)
	v_mfma_f32_16x16x32_bf16 v[14:17], v[164:167], v[184:187], v[14:17]
	s_waitcnt vmcnt(11)
	ds_write_b128 v190, v[82:85] offset:16384
	v_mfma_f32_16x16x32_bf16 v[10:13], v[168:171], v[184:187], v[10:13]
	s_waitcnt vmcnt(10)
	ds_write_b128 v190, v[86:89] offset:20480
	v_mfma_f32_16x16x32_bf16 v[6:9], v[172:175], v[184:187], v[6:9]
	s_waitcnt vmcnt(9)
	ds_write_b128 v190, v[90:93] offset:24576
	v_mfma_f32_16x16x32_bf16 v[2:5], v[176:179], v[184:187], v[2:5]
	s_waitcnt vmcnt(8)
	ds_write_b128 v190, v[94:97] offset:28672
	s_waitcnt lgkmcnt(0)
	s_barrier
	s_add_u32 s0, s0, 0x80
	s_addc_u32 s1, s1, 0
	s_add_u32 s6, s6, 0x80
	s_addc_u32 s7, s7, 0
	s_sub_i32 vcc_lo, vcc_lo, 1
	s_cmp_lg_u32 vcc_lo, 0
	s_cbranch_scc1 .Lgq_c
	ds_read_b128 v[114:117], v188 offset:16384
	ds_read_b128 v[118:121], v188 offset:16896
	ds_read_b128 v[156:159], v188 offset:20480
	ds_read_b128 v[160:163], v188 offset:20992
	ds_read_b128 v[122:125], v112
	ds_read_b128 v[126:129], v112 offset:2048
	s_waitcnt lgkmcnt(1)
	v_mfma_f32_16x16x32_bf16 v[66:69], v[114:117], v[122:125], v[66:69]
	v_mfma_f32_16x16x32_bf16 v[58:61], v[118:121], v[122:125], v[58:61]
	v_mfma_f32_16x16x32_bf16 v[54:57], v[156:159], v[122:125], v[54:57]
	v_mfma_f32_16x16x32_bf16 v[50:53], v[160:163], v[122:125], v[50:53]
	s_waitcnt lgkmcnt(0)
	v_mfma_f32_16x16x32_bf16 v[46:49], v[114:117], v[126:129], v[46:49]
	ds_read_b128 v[180:183], v112 offset:4096
	ds_read_b128 v[184:187], v112 offset:6144
	v_mfma_f32_16x16x32_bf16 v[42:45], v[118:121], v[126:129], v[42:45]
	v_mfma_f32_16x16x32_bf16 v[38:41], v[156:159], v[126:129], v[38:41]
	v_mfma_f32_16x16x32_bf16 v[34:37], v[160:163], v[126:129], v[34:37]
	s_waitcnt lgkmcnt(1)
	v_mfma_f32_16x16x32_bf16 v[30:33], v[114:117], v[180:183], v[30:33]
	ds_read_b128 v[164:167], v189 offset:16384
	ds_read_b128 v[168:171], v189 offset:16896
	v_mfma_f32_16x16x32_bf16 v[26:29], v[118:121], v[180:183], v[26:29]
	v_mfma_f32_16x16x32_bf16 v[22:25], v[156:159], v[180:183], v[22:25]
	ds_read_b128 v[172:175], v189 offset:20480
	ds_read_b128 v[176:179], v189 offset:20992
	v_mfma_f32_16x16x32_bf16 v[18:21], v[160:163], v[180:183], v[18:21]
	s_waitcnt lgkmcnt(4)
	v_mfma_f32_16x16x32_bf16 v[14:17], v[114:117], v[184:187], v[14:17]
	ds_read_b128 v[122:125], v113
	ds_read_b128 v[126:129], v113 offset:2048
	v_mfma_f32_16x16x32_bf16 v[10:13], v[118:121], v[184:187], v[10:13]
	v_mfma_f32_16x16x32_bf16 v[6:9], v[156:159], v[184:187], v[6:9]
	v_mfma_f32_16x16x32_bf16 v[2:5], v[160:163], v[184:187], v[2:5]
	s_waitcnt lgkmcnt(1)
	v_mfma_f32_16x16x32_bf16 v[66:69], v[164:167], v[122:125], v[66:69]
	v_mfma_f32_16x16x32_bf16 v[58:61], v[168:171], v[122:125], v[58:61]
	v_mfma_f32_16x16x32_bf16 v[54:57], v[172:175], v[122:125], v[54:57]
	v_mfma_f32_16x16x32_bf16 v[50:53], v[176:179], v[122:125], v[50:53]
	s_waitcnt lgkmcnt(0)
	v_mfma_f32_16x16x32_bf16 v[46:49], v[164:167], v[126:129], v[46:49]
	ds_read_b128 v[180:183], v113 offset:4096
	ds_read_b128 v[184:187], v113 offset:6144
	v_mfma_f32_16x16x32_bf16 v[42:45], v[168:171], v[126:129], v[42:45]
	v_mfma_f32_16x16x32_bf16 v[38:41], v[172:175], v[126:129], v[38:41]
	v_mfma_f32_16x16x32_bf16 v[34:37], v[176:179], v[126:129], v[34:37]
	s_waitcnt lgkmcnt(1)
	v_mfma_f32_16x16x32_bf16 v[30:33], v[164:167], v[180:183], v[30:33]
	s_waitcnt vmcnt(7)
	ds_write_b128 v110, v[224:227] offset:32768
	v_mfma_f32_16x16x32_bf16 v[26:29], v[168:171], v[180:183], v[26:29]
	s_waitcnt vmcnt(6)
	ds_write_b128 v110, v[228:231] offset:36864
	v_mfma_f32_16x16x32_bf16 v[22:25], v[172:175], v[180:183], v[22:25]
	s_waitcnt vmcnt(5)
	ds_write_b128 v110, v[232:235] offset:40960
	v_mfma_f32_16x16x32_bf16 v[18:21], v[176:179], v[180:183], v[18:21]
	s_waitcnt vmcnt(4)
	ds_write_b128 v110, v[236:239] offset:45056
	s_waitcnt lgkmcnt(4)
	v_mfma_f32_16x16x32_bf16 v[14:17], v[164:167], v[184:187], v[14:17]
	s_waitcnt vmcnt(3)
	ds_write_b128 v190, v[240:243] offset:49168
	v_mfma_f32_16x16x32_bf16 v[10:13], v[168:171], v[184:187], v[10:13]
	s_waitcnt vmcnt(2)
	ds_write_b128 v190, v[244:247] offset:53264
	v_mfma_f32_16x16x32_bf16 v[6:9], v[172:175], v[184:187], v[6:9]
	s_waitcnt vmcnt(1)
	ds_write_b128 v190, v[248:251] offset:57360
	v_mfma_f32_16x16x32_bf16 v[2:5], v[176:179], v[184:187], v[2:5]
	s_waitcnt vmcnt(0)
	ds_write_b128 v190, v[252:255] offset:61456
	s_waitcnt lgkmcnt(0)
	s_barrier
	ds_read_b128 v[114:117], v188 offset:49168
	ds_read_b128 v[118:121], v188 offset:49680
	ds_read_b128 v[156:159], v188 offset:53264
	ds_read_b128 v[160:163], v188 offset:53776
	ds_read_b128 v[122:125], v112 offset:32768
	ds_read_b128 v[126:129], v112 offset:34816
	s_waitcnt lgkmcnt(1)
	v_mfma_f32_16x16x32_bf16 v[66:69], v[114:117], v[122:125], v[66:69]
	v_mfma_f32_16x16x32_bf16 v[58:61], v[118:121], v[122:125], v[58:61]
	v_mfma_f32_16x16x32_bf16 v[54:57], v[156:159], v[122:125], v[54:57]
	v_mfma_f32_16x16x32_bf16 v[50:53], v[160:163], v[122:125], v[50:53]
	s_waitcnt lgkmcnt(0)
	v_mfma_f32_16x16x32_bf16 v[46:49], v[114:117], v[126:129], v[46:49]
	ds_read_b128 v[180:183], v112 offset:36864
	ds_read_b128 v[184:187], v112 offset:38912
	v_mfma_f32_16x16x32_bf16 v[42:45], v[118:121], v[126:129], v[42:45]
	v_mfma_f32_16x16x32_bf16 v[38:41], v[156:159], v[126:129], v[38:41]
	v_mfma_f32_16x16x32_bf16 v[34:37], v[160:163], v[126:129], v[34:37]
	s_waitcnt lgkmcnt(1)
	v_mfma_f32_16x16x32_bf16 v[30:33], v[114:117], v[180:183], v[30:33]
	ds_read_b128 v[164:167], v189 offset:49168
	ds_read_b128 v[168:171], v189 offset:49680
	v_mfma_f32_16x16x32_bf16 v[26:29], v[118:121], v[180:183], v[26:29]
	v_mfma_f32_16x16x32_bf16 v[22:25], v[156:159], v[180:183], v[22:25]
	ds_read_b128 v[172:175], v189 offset:53264
	ds_read_b128 v[176:179], v189 offset:53776
	v_mfma_f32_16x16x32_bf16 v[18:21], v[160:163], v[180:183], v[18:21]
	s_waitcnt lgkmcnt(4)
	v_mfma_f32_16x16x32_bf16 v[14:17], v[114:117], v[184:187], v[14:17]
	ds_read_b128 v[122:125], v113 offset:32768
	ds_read_b128 v[126:129], v113 offset:34816
	v_mfma_f32_16x16x32_bf16 v[10:13], v[118:121], v[184:187], v[10:13]
	v_mfma_f32_16x16x32_bf16 v[6:9], v[156:159], v[184:187], v[6:9]
	v_mfma_f32_16x16x32_bf16 v[2:5], v[160:163], v[184:187], v[2:5]
	s_waitcnt lgkmcnt(1)
	v_mfma_f32_16x16x32_bf16 v[66:69], v[164:167], v[122:125], v[66:69]
	v_mfma_f32_16x16x32_bf16 v[58:61], v[168:171], v[122:125], v[58:61]
	v_mfma_f32_16x16x32_bf16 v[54:57], v[172:175], v[122:125], v[54:57]
	v_mfma_f32_16x16x32_bf16 v[50:53], v[176:179], v[122:125], v[50:53]
	s_waitcnt lgkmcnt(0)
	v_mfma_f32_16x16x32_bf16 v[46:49], v[164:167], v[126:129], v[46:49]
	ds_read_b128 v[180:183], v113 offset:36864
	ds_read_b128 v[184:187], v113 offset:38912
	v_mfma_f32_16x16x32_bf16 v[42:45], v[168:171], v[126:129], v[42:45]
	v_mfma_f32_16x16x32_bf16 v[38:41], v[172:175], v[126:129], v[38:41]
	v_mfma_f32_16x16x32_bf16 v[34:37], v[176:179], v[126:129], v[34:37]
	s_waitcnt lgkmcnt(1)
	v_mfma_f32_16x16x32_bf16 v[30:33], v[164:167], v[180:183], v[30:33]
	v_mfma_f32_16x16x32_bf16 v[26:29], v[168:171], v[180:183], v[26:29]
	v_mfma_f32_16x16x32_bf16 v[22:25], v[172:175], v[180:183], v[22:25]
	v_mfma_f32_16x16x32_bf16 v[18:21], v[176:179], v[180:183], v[18:21]
	s_waitcnt lgkmcnt(0)
	v_mfma_f32_16x16x32_bf16 v[14:17], v[164:167], v[184:187], v[14:17]
	v_mfma_f32_16x16x32_bf16 v[10:13], v[168:171], v[184:187], v[10:13]
	v_mfma_f32_16x16x32_bf16 v[6:9], v[172:175], v[184:187], v[6:9]
	v_mfma_f32_16x16x32_bf16 v[2:5], v[176:179], v[184:187], v[2:5]
	s_barrier

.LBB0_521:
	s_cmp_lt_i32 s41, 6
	s_cbranch_scc0 .LBB0_203
	s_lshl_b32 s0, s41, 6
	s_and_b32 s0, s0, 64
	s_add_i32 s12, s42, s0
	v_mov_b32_e32 v1, v0
	s_lshl_b32 s13, s12, 6
	s_ashr_i32 s41, s41, 1
	s_lshl_b32 s14, s41, 7
	s_waitcnt vmcnt(4)
	v_ashrrev_i32_e32 v8, 3, v1
	v_and_b32_e32 v9, 7, v1
	v_add_u32_e32 v4, s13, v8
	v_mov_b64_e32 v[2:3], s[66:67]
	s_addk_i32 s14, 0xc00
	v_mad_i64_i32 v[2:3], s[0:1], v4, s58, v[2:3]
	v_lshlrev_b32_e32 v106, 4, v9
	v_lshl_add_u64 v[58:59], v[2:3], 0, v[106:107]
	v_add_u32_e32 v4, s14, v8
	v_mov_b64_e32 v[2:3], s[2:3]
	v_mad_i64_i32 v[2:3], s[0:1], v4, s58, v[2:3]
	s_mov_b32 s0, 0x11000
	s_nop 0
	v_add_co_u32_e32 v4, vcc, s0, v58
	v_lshl_add_u64 v[60:61], v[2:3], 0, v[106:107]
	s_nop 0
	v_addc_co_u32_e32 v5, vcc, 0, v59, vcc
	v_add_co_u32_e32 v2, vcc, s0, v60
	s_mov_b32 s0, 0x22000
	s_nop 0
	v_addc_co_u32_e32 v3, vcc, 0, v61, vcc
	v_add_co_u32_e32 v6, vcc, s0, v60
	s_mov_b32 s0, 0x33000
	s_nop 0
	v_addc_co_u32_e32 v7, vcc, 0, v61, vcc
	global_load_dwordx4 v[34:37], v[58:59], off
	global_load_dwordx4 v[38:41], v[60:61], off
	global_load_dwordx4 v[42:45], v[2:3], off
	global_load_dwordx4 v[50:53], v[6:7], off
	v_add_co_u32_e32 v2, vcc, s0, v60
	s_waitcnt vmcnt(7)
	v_ashrrev_i32_e32 v11, 4, v1
	v_addc_co_u32_e32 v3, vcc, 0, v61, vcc
	global_load_dwordx4 v[54:57], v[2:3], off
	global_load_dwordx4 v[46:49], v[4:5], off
	v_lshrrev_b32_e32 v12, 5, v1
	v_lshrrev_b32_e32 v10, 4, v1
	v_bfe_u32 v62, v1, 4, 2
	v_bfe_u32 v13, v1, 1, 3
	s_waitcnt vmcnt(8)
	v_xor_b32_e32 v16, v11, v1
	v_and_b32_e32 v11, 1, v11
	v_and_b32_e32 v12, 6, v12
	v_ashrrev_i32_e32 v63, 7, v1
	v_lshlrev_b32_e32 v65, 7, v8
	v_bitop3_b32 v8, v10, v13, 3 bitop3:0x6c
	v_bitop3_b32 v13, v62, v13, 4 bitop3:0x36
	v_bitop3_b32 v9, v11, v9, v12 bitop3:0x36
	v_and_b32_e32 v64, 15, v1
	v_lshlrev_b32_e32 v14, 1, v1
	v_and_b32_e32 v15, 0x43, v1
	v_lshlrev_b32_e32 v10, 12, v63
	v_lshlrev_b32_e32 v66, 4, v8
	v_lshlrev_b32_e32 v68, 4, v13
	v_lshlrev_b32_e32 v70, 4, v9
	v_mov_b32_e32 v2, 0
	v_lshlrev_b32_e32 v17, 7, v64
	v_and_or_b32 v14, v14, 24, v15
	v_lshlrev_b32_e32 v11, 4, v16
	s_movk_i32 s4, 0x70
	v_or_b32_e32 v8, v66, v10
	v_or_b32_e32 v9, v68, v10
	v_or_b32_e32 v10, v65, v70
	s_mov_b64 s[0:1], 0
	v_lshrrev_b32_e32 v220, 3, v0
	v_and_b32_e32 v221, 7, v0
	s_movk_i32 vcc_lo, 0x880
	v_mul_lo_u32 v220, v220, vcc_lo
	v_lshl_add_u32 v216, v221, 4, v220
	v_add_u32_e32 v217, 0x11000, v216
	v_add_u32_e32 v218, 0x22000, v216
	v_add_u32_e32 v219, 0x33000, v216
	s_mul_i32 s0, s13, vcc_lo
	s_add_u32 s0, s66, s0
	s_addc_u32 s1, s67, 0
	s_mul_i32 s6, s14, vcc_lo
	s_add_u32 s6, s2, s6
	s_addc_u32 s7, s3, 0
	global_load_dwordx4 v[224:227], v216, s[0:1] offset:128
	global_load_dwordx4 v[228:231], v217, s[0:1] offset:128
	global_load_dwordx4 v[232:235], v216, s[6:7] offset:128
	global_load_dwordx4 v[236:239], v217, s[6:7] offset:128
	global_load_dwordx4 v[240:243], v218, s[6:7] offset:128
	global_load_dwordx4 v[244:247], v219, s[6:7] offset:128
	v_mov_b32_e32 v3, v2
	v_mov_b32_e32 v4, v2
	v_mov_b32_e32 v5, v2
	v_mov_b32_e32 v6, v2
	v_mov_b32_e32 v7, v2
	v_lshlrev_b32_e32 v67, 7, v14
	v_and_or_b32 v69, v11, s4, v65
	v_add_u32_e32 v71, v8, v17
	v_add_u32_e32 v72, v9, v17
	v_mov_b32_e32 v8, v2
	v_mov_b32_e32 v9, v2
	v_mov_b32_e32 v11, v2
	v_mov_b32_e32 v12, v2
	v_mov_b32_e32 v13, v2
	v_mov_b32_e32 v14, v2
	v_mov_b32_e32 v15, v2
	v_mov_b32_e32 v16, v2
	v_mov_b32_e32 v17, v2
	v_mov_b32_e32 v18, v2
	v_mov_b32_e32 v19, v2
	v_mov_b32_e32 v20, v2
	v_mov_b32_e32 v21, v2
	v_mov_b32_e32 v22, v2
	s_waitcnt vmcnt(10)
	ds_write_b128 v10, v[38:41] offset:16384
	ds_write_b128 v69, v[34:37]
	s_waitcnt vmcnt(9)
	ds_write_b128 v10, v[42:45] offset:20480
	s_waitcnt vmcnt(8)
	ds_write_b128 v10, v[50:53] offset:24576
	s_waitcnt vmcnt(7)
	ds_write_b128 v10, v[54:57] offset:28672
	s_waitcnt vmcnt(6)
	ds_write_b128 v69, v[46:49] offset:4096
	v_mov_b32_e32 v10, v2
	v_mov_b32_e32 v23, v2
	v_mov_b32_e32 v24, v2
	v_mov_b32_e32 v25, v2
	v_mov_b32_e32 v26, v2
	v_mov_b32_e32 v27, v2
	v_mov_b32_e32 v28, v2
	v_mov_b32_e32 v29, v2
	v_mov_b32_e32 v30, v2
	v_mov_b32_e32 v31, v2
	v_mov_b32_e32 v32, v2
	v_mov_b32_e32 v33, v2
	v_add_u32_e32 v188, v66, v67
	v_add_u32_e32 v189, v68, v67
	v_add_u32_e32 v190, v65, v70
	s_waitcnt lgkmcnt(0)
	s_barrier
	s_branch .LBB0_524

.Lgq_h:
	ds_read_b128 v[74:77], v188 offset:16384
	ds_read_b128 v[78:81], v188 offset:16896
	ds_read_b128 v[90:93], v188 offset:20480
	ds_read_b128 v[94:97], v188 offset:20992
	ds_read_b128 v[82:85], v71
	ds_read_b128 v[86:89], v71 offset:2048
	ds_read_b128 v[164:167], v189 offset:16384
	ds_read_b128 v[168:171], v189 offset:16896
	ds_read_b128 v[180:183], v72
	global_load_dwordx4 v[34:37], v216, s[0:1] offset:256
	global_load_dwordx4 v[46:49], v217, s[0:1] offset:256
	s_waitcnt lgkmcnt(4)
	v_mfma_f32_16x16x32_bf16 v[30:33], v[74:77], v[82:85], v[30:33]
	ds_read_b128 v[172:175], v189 offset:20480
	ds_read_b128 v[176:179], v189 offset:20992
	v_mfma_f32_16x16x32_bf16 v[26:29], v[78:81], v[82:85], v[26:29]
	global_load_dwordx4 v[38:41], v216, s[6:7] offset:256
	v_mfma_f32_16x16x32_bf16 v[22:25], v[90:93], v[82:85], v[22:25]
	ds_read_b128 v[184:187], v72 offset:2048
	v_mfma_f32_16x16x32_bf16 v[18:21], v[94:97], v[82:85], v[18:21]
	global_load_dwordx4 v[42:45], v217, s[6:7] offset:256
	s_waitcnt lgkmcnt(6)
	v_mfma_f32_16x16x32_bf16 v[14:17], v[74:77], v[86:89], v[14:17]
	global_load_dwordx4 v[50:53], v218, s[6:7] offset:256
	v_mfma_f32_16x16x32_bf16 v[10:13], v[78:81], v[86:89], v[10:13]
	v_mfma_f32_16x16x32_bf16 v[6:9], v[90:93], v[86:89], v[6:9]
	global_load_dwordx4 v[54:57], v219, s[6:7] offset:256
	v_mfma_f32_16x16x32_bf16 v[2:5], v[94:97], v[86:89], v[2:5]
	s_waitcnt lgkmcnt(1)
	v_mfma_f32_16x16x32_bf16 v[30:33], v[164:167], v[180:183], v[30:33]
	s_waitcnt vmcnt(11)
	ds_write_b128 v69, v[224:227] offset:32768
	v_mfma_f32_16x16x32_bf16 v[26:29], v[168:171], v[180:183], v[26:29]
	s_waitcnt vmcnt(10)
	ds_write_b128 v69, v[228:231] offset:36864
	v_mfma_f32_16x16x32_bf16 v[22:25], v[172:175], v[180:183], v[22:25]
	s_waitcnt vmcnt(9)
	ds_write_b128 v190, v[232:235] offset:49168
	v_mfma_f32_16x16x32_bf16 v[18:21], v[176:179], v[180:183], v[18:21]
	s_waitcnt vmcnt(8)
	ds_write_b128 v190, v[236:239] offset:53264
	s_waitcnt lgkmcnt(4)
	v_mfma_f32_16x16x32_bf16 v[14:17], v[164:167], v[184:187], v[14:17]
	s_waitcnt vmcnt(7)
	ds_write_b128 v190, v[240:243] offset:57360
	v_mfma_f32_16x16x32_bf16 v[10:13], v[168:171], v[184:187], v[10:13]
	s_waitcnt vmcnt(6)
	ds_write_b128 v190, v[244:247] offset:61456
	v_mfma_f32_16x16x32_bf16 v[6:9], v[172:175], v[184:187], v[6:9]
	v_mfma_f32_16x16x32_bf16 v[2:5], v[176:179], v[184:187], v[2:5]
	s_waitcnt lgkmcnt(0)
	s_barrier
	s_add_u32 s0, s0, 0x80
	s_addc_u32 s1, s1, 0
	s_add_u32 s6, s6, 0x80
	s_addc_u32 s7, s7, 0
	ds_read_b128 v[74:77], v188 offset:49168
	ds_read_b128 v[78:81], v188 offset:49680
	ds_read_b128 v[90:93], v188 offset:53264
	ds_read_b128 v[94:97], v188 offset:53776
	ds_read_b128 v[82:85], v71 offset:32768
	ds_read_b128 v[86:89], v71 offset:34816
	ds_read_b128 v[164:167], v189 offset:49168
	ds_read_b128 v[168:171], v189 offset:49680
	ds_read_b128 v[180:183], v72 offset:32768
	global_load_dwordx4 v[224:227], v216, s[0:1] offset:256
	global_load_dwordx4 v[228:231], v217, s[0:1] offset:256
	s_waitcnt lgkmcnt(4)
	v_mfma_f32_16x16x32_bf16 v[30:33], v[74:77], v[82:85], v[30:33]
	ds_read_b128 v[172:175], v189 offset:53264
	ds_read_b128 v[176:179], v189 offset:53776
	v_mfma_f32_16x16x32_bf16 v[26:29], v[78:81], v[82:85], v[26:29]
	global_load_dwordx4 v[232:235], v216, s[6:7] offset:256
	v_mfma_f32_16x16x32_bf16 v[22:25], v[90:93], v[82:85], v[22:25]
	ds_read_b128 v[184:187], v72 offset:34816
	v_mfma_f32_16x16x32_bf16 v[18:21], v[94:97], v[82:85], v[18:21]
	global_load_dwordx4 v[236:239], v217, s[6:7] offset:256
	s_waitcnt lgkmcnt(6)
	v_mfma_f32_16x16x32_bf16 v[14:17], v[74:77], v[86:89], v[14:17]
	global_load_dwordx4 v[240:243], v218, s[6:7] offset:256
	v_mfma_f32_16x16x32_bf16 v[10:13], v[78:81], v[86:89], v[10:13]
	v_mfma_f32_16x16x32_bf16 v[6:9], v[90:93], v[86:89], v[6:9]
	global_load_dwordx4 v[244:247], v219, s[6:7] offset:256
	v_mfma_f32_16x16x32_bf16 v[2:5], v[94:97], v[86:89], v[2:5]
	s_waitcnt lgkmcnt(1)
	v_mfma_f32_16x16x32_bf16 v[30:33], v[164:167], v[180:183], v[30:33]
	s_waitcnt vmcnt(11)
	ds_write_b128 v69, v[34:37]
	v_mfma_f32_16x16x32_bf16 v[26:29], v[168:171], v[180:183], v[26:29]
	s_waitcnt vmcnt(10)
	ds_write_b128 v69, v[46:49] offset:4096
	v_mfma_f32_16x16x32_bf16 v[22:25], v[172:175], v[180:183], v[22:25]
	s_waitcnt vmcnt(9)
	ds_write_b128 v190, v[38:41] offset:16384
	v_mfma_f32_16x16x32_bf16 v[18:21], v[176:179], v[180:183], v[18:21]
	s_waitcnt vmcnt(8)
	ds_write_b128 v190, v[42:45] offset:20480
	s_waitcnt lgkmcnt(4)
	v_mfma_f32_16x16x32_bf16 v[14:17], v[164:167], v[184:187], v[14:17]
	s_waitcnt vmcnt(7)
	ds_write_b128 v190, v[50:53] offset:24576
	v_mfma_f32_16x16x32_bf16 v[10:13], v[168:171], v[184:187], v[10:13]
	s_waitcnt vmcnt(6)
	ds_write_b128 v190, v[54:57] offset:28672
	v_mfma_f32_16x16x32_bf16 v[6:9], v[172:175], v[184:187], v[6:9]
	v_mfma_f32_16x16x32_bf16 v[2:5], v[176:179], v[184:187], v[2:5]
	s_waitcnt lgkmcnt(0)
	s_barrier
	s_add_u32 s0, s0, 0x80
	s_addc_u32 s1, s1, 0
	s_add_u32 s6, s6, 0x80
	s_addc_u32 s7, s7, 0
	s_sub_i32 vcc_lo, vcc_lo, 1
	s_cmp_lg_u32 vcc_lo, 0
	s_cbranch_scc1 .Lgq_h
	ds_read_b128 v[74:77], v188 offset:16384
	ds_read_b128 v[78:81], v188 offset:16896
	ds_read_b128 v[90:93], v188 offset:20480
	ds_read_b128 v[94:97], v188 offset:20992
	ds_read_b128 v[82:85], v71
	ds_read_b128 v[86:89], v71 offset:2048
	ds_read_b128 v[164:167], v189 offset:16384
	ds_read_b128 v[168:171], v189 offset:16896
	ds_read_b128 v[180:183], v72
	s_waitcnt lgkmcnt(4)
	v_mfma_f32_16x16x32_bf16 v[30:33], v[74:77], v[82:85], v[30:33]
	ds_read_b128 v[172:175], v189 offset:20480
	ds_read_b128 v[176:179], v189 offset:20992
	v_mfma_f32_16x16x32_bf16 v[26:29], v[78:81], v[82:85], v[26:29]
	v_mfma_f32_16x16x32_bf16 v[22:25], v[90:93], v[82:85], v[22:25]
	ds_read_b128 v[184:187], v72 offset:2048
	v_mfma_f32_16x16x32_bf16 v[18:21], v[94:97], v[82:85], v[18:21]
	s_waitcnt lgkmcnt(6)
	v_mfma_f32_16x16x32_bf16 v[14:17], v[74:77], v[86:89], v[14:17]
	v_mfma_f32_16x16x32_bf16 v[10:13], v[78:81], v[86:89], v[10:13]
	v_mfma_f32_16x16x32_bf16 v[6:9], v[90:93], v[86:89], v[6:9]
	v_mfma_f32_16x16x32_bf16 v[2:5], v[94:97], v[86:89], v[2:5]
	s_waitcnt lgkmcnt(1)
	v_mfma_f32_16x16x32_bf16 v[30:33], v[164:167], v[180:183], v[30:33]
	s_waitcnt vmcnt(5)
	ds_write_b128 v69, v[224:227] offset:32768
	v_mfma_f32_16x16x32_bf16 v[26:29], v[168:171], v[180:183], v[26:29]
	s_waitcnt vmcnt(4)
	ds_write_b128 v69, v[228:231] offset:36864
	v_mfma_f32_16x16x32_bf16 v[22:25], v[172:175], v[180:183], v[22:25]
	s_waitcnt vmcnt(3)
	ds_write_b128 v190, v[232:235] offset:49168
	v_mfma_f32_16x16x32_bf16 v[18:21], v[176:179], v[180:183], v[18:21]
	s_waitcnt vmcnt(2)
	ds_write_b128 v190, v[236:239] offset:53264
	s_waitcnt lgkmcnt(4)
	v_mfma_f32_16x16x32_bf16 v[14:17], v[164:167], v[184:187], v[14:17]
	s_waitcnt vmcnt(1)
	ds_write_b128 v190, v[240:243] offset:57360
	v_mfma_f32_16x16x32_bf16 v[10:13], v[168:171], v[184:187], v[10:13]
	s_waitcnt vmcnt(0)
	ds_write_b128 v190, v[244:247] offset:61456
	v_mfma_f32_16x16x32_bf16 v[6:9], v[172:175], v[184:187], v[6:9]
	v_mfma_f32_16x16x32_bf16 v[2:5], v[176:179], v[184:187], v[2:5]
	s_waitcnt lgkmcnt(0)
	s_barrier
	ds_read_b128 v[74:77], v188 offset:49168
	ds_read_b128 v[78:81], v188 offset:49680
	ds_read_b128 v[90:93], v188 offset:53264
	ds_read_b128 v[94:97], v188 offset:53776
	ds_read_b128 v[82:85], v71 offset:32768
	ds_read_b128 v[86:89], v71 offset:34816
	ds_read_b128 v[164:167], v189 offset:49168
	ds_read_b128 v[168:171], v189 offset:49680
	ds_read_b128 v[180:183], v72 offset:32768
	s_waitcnt lgkmcnt(4)
	v_mfma_f32_16x16x32_bf16 v[30:33], v[74:77], v[82:85], v[30:33]
	ds_read_b128 v[172:175], v189 offset:53264
	ds_read_b128 v[176:179], v189 offset:53776
	v_mfma_f32_16x16x32_bf16 v[26:29], v[78:81], v[82:85], v[26:29]
	v_mfma_f32_16x16x32_bf16 v[22:25], v[90:93], v[82:85], v[22:25]
	ds_read_b128 v[184:187], v72 offset:34816
	v_mfma_f32_16x16x32_bf16 v[18:21], v[94:97], v[82:85], v[18:21]
	s_waitcnt lgkmcnt(6)
	v_mfma_f32_16x16x32_bf16 v[14:17], v[74:77], v[86:89], v[14:17]
	v_mfma_f32_16x16x32_bf16 v[10:13], v[78:81], v[86:89], v[10:13]
	v_mfma_f32_16x16x32_bf16 v[6:9], v[90:93], v[86:89], v[6:9]
	v_mfma_f32_16x16x32_bf16 v[2:5], v[94:97], v[86:89], v[2:5]
	s_waitcnt lgkmcnt(1)
	v_mfma_f32_16x16x32_bf16 v[30:33], v[164:167], v[180:183], v[30:33]
	v_mfma_f32_16x16x32_bf16 v[26:29], v[168:171], v[180:183], v[26:29]
	v_mfma_f32_16x16x32_bf16 v[22:25], v[172:175], v[180:183], v[22:25]
	v_mfma_f32_16x16x32_bf16 v[18:21], v[176:179], v[180:183], v[18:21]
	s_waitcnt lgkmcnt(0)
	v_mfma_f32_16x16x32_bf16 v[14:17], v[164:167], v[184:187], v[14:17]
	v_mfma_f32_16x16x32_bf16 v[10:13], v[168:171], v[184:187], v[10:13]
	v_mfma_f32_16x16x32_bf16 v[6:9], v[172:175], v[184:187], v[6:9]
	v_mfma_f32_16x16x32_bf16 v[2:5], v[176:179], v[184:187], v[2:5]
	s_barrier

.LBB0_1384:
	s_abs_i32 s11, s39
	s_mul_hi_u32 s12, s11, s46
	s_mul_i32 s13, s12, s43
	s_ashr_i32 s10, s39, 31
	s_sub_i32 s11, s11, s13
	s_xor_b32 s10, s10, s45
	s_add_i32 s13, s12, 1
	s_sub_i32 s14, s11, s43
	s_cmp_ge_u32 s11, s43
	s_cselect_b32 s12, s13, s12
	s_cselect_b32 s11, s14, s11
	s_add_i32 s13, s12, 1
	s_cmp_ge_u32 s11, s43
	s_cselect_b32 s11, s13, s12
	s_xor_b32 s11, s11, s10
	s_sub_i32 s10, s11, s10
	v_mov_b32_e32 v1, v0
	s_lshl_b32 s47, s10, 7
	s_mul_i32 s10, s10, s40
	s_sub_i32 s10, s39, s10
	s_waitcnt vmcnt(1)
	v_ashrrev_i32_e32 v34, 3, v1
	v_and_b32_e32 v35, 7, v1
	v_add_u32_e32 v4, s47, v34
	v_mov_b64_e32 v[2:3], s[66:67]
	s_lshl_b32 s48, s10, 10
	v_mad_i64_i32 v[2:3], s[10:11], v4, s58, v[2:3]
	v_lshlrev_b32_e32 v106, 4, v35
	v_lshl_add_u64 v[98:99], v[2:3], 0, v[106:107]
	s_mov_b32 s4, 0x11000
	v_add_co_u32_e32 v6, vcc, s4, v98
	s_mov_b32 s5, 0x22000
	s_nop 0
	v_addc_co_u32_e32 v7, vcc, 0, v99, vcc
	s_add_i32 s48, s48, s44
	v_add_co_u32_e32 v10, vcc, s5, v98
	v_add_u32_e32 v4, s48, v34
	v_mov_b64_e32 v[2:3], s[0:1]
	v_addc_co_u32_e32 v11, vcc, 0, v99, vcc
	s_mov_b32 s8, 0x33000
	v_mad_i64_i32 v[18:19], s[10:11], v4, s58, v[2:3]
	v_add_co_u32_e32 v14, vcc, s8, v98
	v_lshl_add_u64 v[100:101], v[18:19], 0, v[106:107]
	s_nop 0
	v_addc_co_u32_e32 v15, vcc, 0, v99, vcc
	v_add_co_u32_e32 v22, vcc, s4, v100
	global_load_dwordx4 v[2:5], v[98:99], off
	s_nop 0
	v_addc_co_u32_e32 v23, vcc, 0, v101, vcc
	v_add_co_u32_e32 v26, vcc, s5, v100
	global_load_dwordx4 v[6:9], v[6:7], off
	s_nop 0
	global_load_dwordx4 v[10:13], v[10:11], off
	v_addc_co_u32_e32 v27, vcc, 0, v101, vcc
	global_load_dwordx4 v[14:17], v[14:15], off
	v_add_co_u32_e32 v30, vcc, s8, v100
	global_load_dwordx4 v[18:21], v[100:101], off
	s_nop 0
	global_load_dwordx4 v[22:25], v[22:23], off
	s_nop 0
	global_load_dwordx4 v[26:29], v[26:27], off
	v_addc_co_u32_e32 v31, vcc, 0, v101, vcc
	global_load_dwordx4 v[30:33], v[30:31], off
	v_ashrrev_i32_e32 v37, 4, v1
	s_waitcnt vmcnt(8)
	v_lshrrev_b32_e32 v38, 5, v1
	v_xor_b32_e32 v41, v37, v1
	v_and_b32_e32 v37, 1, v37
	v_and_b32_e32 v38, 6, v38
	v_lshrrev_b32_e32 v36, 4, v1
	v_bfe_u32 v39, v1, 1, 3
	v_bitop3_b32 v35, v37, v35, v38 bitop3:0x36
	v_lshlrev_b32_e32 v105, 7, v34
	v_bitop3_b32 v34, v36, v39, 3 bitop3:0x6c
	v_lshlrev_b32_e32 v37, 4, v41
	s_movk_i32 s4, 0x70
	v_lshlrev_b32_e32 v109, 4, v35
	v_lshlrev_b32_e32 v106, 4, v34
	v_and_or_b32 v108, v37, s4, v105
	v_or_b32_e32 v34, v105, v109
	v_lshlrev_b32_e32 v40, 1, v1
	v_bfe_u32 v102, v1, 4, 2
	v_ashrrev_i32_e32 v103, 7, v1
	v_and_b32_e32 v104, 15, v1
	v_lshlrev_b32_e32 v36, 13, v103
	v_lshlrev_b32_e32 v42, 7, v104
	v_or_b32_e32 v35, v106, v36
	s_mov_b64 s[10:11], 0
	v_lshrrev_b32_e32 v220, 3, v0
	v_and_b32_e32 v221, 7, v0
	s_movk_i32 vcc_lo, 0x880
	v_mul_lo_u32 v220, v220, vcc_lo
	v_lshl_add_u32 v216, v221, 4, v220
	v_add_u32_e32 v217, 0x11000, v216
	v_add_u32_e32 v218, 0x22000, v216
	v_add_u32_e32 v219, 0x33000, v216
	s_mul_i32 s10, s47, vcc_lo
	s_add_u32 s10, s66, s10
	s_addc_u32 s11, s67, 0
	s_mul_i32 s28, s48, vcc_lo
	s_add_u32 s28, s0, s28
	s_addc_u32 s29, s1, 0
	global_load_dwordx4 v[224:227], v216, s[10:11] offset:128
	global_load_dwordx4 v[228:231], v217, s[10:11] offset:128
	global_load_dwordx4 v[232:235], v218, s[10:11] offset:128
	global_load_dwordx4 v[236:239], v219, s[10:11] offset:128
	global_load_dwordx4 v[240:243], v216, s[28:29] offset:128
	global_load_dwordx4 v[244:247], v217, s[28:29] offset:128
	global_load_dwordx4 v[248:251], v218, s[28:29] offset:128
	global_load_dwordx4 v[252:255], v219, s[28:29] offset:128
	v_add_u32_e32 v112, v35, v42
	s_waitcnt vmcnt(15)
	ds_write_b128 v108, v[2:5]
	s_waitcnt vmcnt(14)
	ds_write_b128 v108, v[6:9] offset:4096
	s_waitcnt vmcnt(13)
	ds_write_b128 v108, v[10:13] offset:8192
	s_waitcnt vmcnt(12)
	ds_write_b128 v108, v[14:17] offset:12288
	s_waitcnt vmcnt(11)
	ds_write_b128 v34, v[18:21] offset:16384
	s_waitcnt vmcnt(10)
	ds_write_b128 v34, v[22:25] offset:20480
	s_waitcnt vmcnt(9)
	ds_write_b128 v34, v[26:29] offset:24576
	s_waitcnt vmcnt(8)
	ds_write_b128 v34, v[30:33] offset:28672
	v_and_b32_e32 v34, 0x43, v1
	v_and_or_b32 v34, v40, 24, v34
	v_lshlrev_b32_e32 v110, 7, v34
	v_bitop3_b32 v34, v102, v39, 4 bitop3:0x36
	v_lshlrev_b32_e32 v111, 4, v34
	v_or_b32_e32 v36, v111, v36
	v_mov_b32_e32 v34, 0
	v_add_u32_e32 v113, v36, v42
	v_mov_b32_e32 v35, v34
	v_mov_b32_e32 v36, v34
	v_mov_b32_e32 v37, v34
	v_mov_b32_e32 v38, v34
	v_mov_b32_e32 v39, v34
	v_mov_b32_e32 v40, v34
	v_mov_b32_e32 v41, v34
	v_mov_b32_e32 v42, v34
	v_mov_b32_e32 v43, v34
	v_mov_b32_e32 v44, v34
	v_mov_b32_e32 v45, v34
	v_mov_b32_e32 v46, v34
	v_mov_b32_e32 v47, v34
	v_mov_b32_e32 v48, v34
	v_mov_b32_e32 v49, v34
	v_mov_b32_e32 v50, v34
	v_mov_b32_e32 v51, v34
	v_mov_b32_e32 v52, v34
	v_mov_b32_e32 v53, v34
	v_mov_b32_e32 v54, v34
	v_mov_b32_e32 v55, v34
	v_mov_b32_e32 v56, v34
	v_mov_b32_e32 v57, v34
	v_mov_b32_e32 v58, v34
	v_mov_b32_e32 v59, v34
	v_mov_b32_e32 v60, v34
	v_mov_b32_e32 v61, v34
	v_mov_b32_e32 v62, v34
	v_mov_b32_e32 v63, v34
	v_mov_b32_e32 v64, v34
	v_mov_b32_e32 v65, v34
	v_mov_b32_e32 v66, v34
	v_mov_b32_e32 v67, v34
	v_mov_b32_e32 v68, v34
	v_mov_b32_e32 v69, v34
	v_mov_b32_e32 v70, v34
	v_mov_b32_e32 v71, v34
	v_mov_b32_e32 v72, v34
	v_mov_b32_e32 v73, v34
	v_mov_b32_e32 v74, v34
	v_mov_b32_e32 v75, v34
	v_mov_b32_e32 v76, v34
	v_mov_b32_e32 v77, v34
	v_mov_b32_e32 v78, v34
	v_mov_b32_e32 v79, v34
	v_mov_b32_e32 v80, v34
	v_mov_b32_e32 v81, v34
	v_mov_b32_e32 v82, v34
	v_mov_b32_e32 v83, v34
	v_mov_b32_e32 v84, v34
	v_mov_b32_e32 v85, v34
	v_mov_b32_e32 v86, v34
	v_mov_b32_e32 v87, v34
	v_mov_b32_e32 v88, v34
	v_mov_b32_e32 v89, v34
	v_mov_b32_e32 v90, v34
	v_mov_b32_e32 v91, v34
	v_mov_b32_e32 v92, v34
	v_mov_b32_e32 v93, v34
	v_mov_b32_e32 v94, v34
	v_mov_b32_e32 v95, v34
	v_mov_b32_e32 v96, v34
	v_mov_b32_e32 v97, v34
	v_add_u32_e32 v188, v106, v110
	v_add_u32_e32 v189, v111, v110
	v_add_u32_e32 v190, v105, v109
	s_waitcnt lgkmcnt(0)
	s_barrier
	s_branch .LBB0_1386

.Lgq_o:
	ds_read_b128 v[114:117], v188 offset:16384
	ds_read_b128 v[122:125], v188 offset:16896
	ds_read_b128 v[126:129], v188 offset:20480
	ds_read_b128 v[156:159], v188 offset:20992
	ds_read_b128 v[118:121], v112
	ds_read_b128 v[160:163], v112 offset:2048
	global_load_dwordx4 v[2:5], v216, s[10:11] offset:256
	global_load_dwordx4 v[6:9], v217, s[10:11] offset:256
	s_waitcnt lgkmcnt(1)
	v_mfma_f32_16x16x32_bf16 v[94:97], v[114:117], v[118:121], v[94:97]
	v_mfma_f32_16x16x32_bf16 v[90:93], v[122:125], v[118:121], v[90:93]
	global_load_dwordx4 v[10:13], v218, s[10:11] offset:256
	v_mfma_f32_16x16x32_bf16 v[86:89], v[126:129], v[118:121], v[86:89]
	v_mfma_f32_16x16x32_bf16 v[82:85], v[156:159], v[118:121], v[82:85]
	s_waitcnt lgkmcnt(0)
	v_mfma_f32_16x16x32_bf16 v[78:81], v[114:117], v[160:163], v[78:81]
	ds_read_b128 v[180:183], v112 offset:4096
	ds_read_b128 v[184:187], v112 offset:6144
	v_mfma_f32_16x16x32_bf16 v[74:77], v[122:125], v[160:163], v[74:77]
	v_mfma_f32_16x16x32_bf16 v[70:73], v[126:129], v[160:163], v[70:73]
	global_load_dwordx4 v[14:17], v219, s[10:11] offset:256
	v_mfma_f32_16x16x32_bf16 v[66:69], v[156:159], v[160:163], v[66:69]
	s_waitcnt lgkmcnt(1)
	v_mfma_f32_16x16x32_bf16 v[62:65], v[114:117], v[180:183], v[62:65]
	ds_read_b128 v[164:167], v189 offset:16384
	ds_read_b128 v[168:171], v189 offset:16896
	v_mfma_f32_16x16x32_bf16 v[58:61], v[122:125], v[180:183], v[58:61]
	global_load_dwordx4 v[18:21], v216, s[28:29] offset:256
	v_mfma_f32_16x16x32_bf16 v[54:57], v[126:129], v[180:183], v[54:57]
	ds_read_b128 v[172:175], v189 offset:20480
	ds_read_b128 v[176:179], v189 offset:20992
	v_mfma_f32_16x16x32_bf16 v[50:53], v[156:159], v[180:183], v[50:53]
	s_waitcnt lgkmcnt(4)
	v_mfma_f32_16x16x32_bf16 v[46:49], v[114:117], v[184:187], v[46:49]
	ds_read_b128 v[118:121], v113
	ds_read_b128 v[160:163], v113 offset:2048
	v_mfma_f32_16x16x32_bf16 v[42:45], v[122:125], v[184:187], v[42:45]
	v_mfma_f32_16x16x32_bf16 v[38:41], v[126:129], v[184:187], v[38:41]
	global_load_dwordx4 v[22:25], v217, s[28:29] offset:256
	v_mfma_f32_16x16x32_bf16 v[34:37], v[156:159], v[184:187], v[34:37]
	s_waitcnt lgkmcnt(1)
	v_mfma_f32_16x16x32_bf16 v[94:97], v[164:167], v[118:121], v[94:97]
	v_mfma_f32_16x16x32_bf16 v[90:93], v[168:171], v[118:121], v[90:93]
	global_load_dwordx4 v[26:29], v218, s[28:29] offset:256
	v_mfma_f32_16x16x32_bf16 v[86:89], v[172:175], v[118:121], v[86:89]
	v_mfma_f32_16x16x32_bf16 v[82:85], v[176:179], v[118:121], v[82:85]
	s_waitcnt lgkmcnt(0)
	v_mfma_f32_16x16x32_bf16 v[78:81], v[164:167], v[160:163], v[78:81]
	ds_read_b128 v[180:183], v113 offset:4096
	ds_read_b128 v[184:187], v113 offset:6144
	v_mfma_f32_16x16x32_bf16 v[74:77], v[168:171], v[160:163], v[74:77]
	v_mfma_f32_16x16x32_bf16 v[70:73], v[172:175], v[160:163], v[70:73]
	global_load_dwordx4 v[30:33], v219, s[28:29] offset:256
	v_mfma_f32_16x16x32_bf16 v[66:69], v[176:179], v[160:163], v[66:69]
	s_waitcnt lgkmcnt(1)
	v_mfma_f32_16x16x32_bf16 v[62:65], v[164:167], v[180:183], v[62:65]
	s_waitcnt vmcnt(15)
	ds_write_b128 v108, v[224:227] offset:32768
	v_mfma_f32_16x16x32_bf16 v[58:61], v[168:171], v[180:183], v[58:61]
	s_waitcnt vmcnt(14)
	ds_write_b128 v108, v[228:231] offset:36864
	v_mfma_f32_16x16x32_bf16 v[54:57], v[172:175], v[180:183], v[54:57]
	s_waitcnt vmcnt(13)
	ds_write_b128 v108, v[232:235] offset:40960
	v_mfma_f32_16x16x32_bf16 v[50:53], v[176:179], v[180:183], v[50:53]
	s_waitcnt vmcnt(12)
	ds_write_b128 v108, v[236:239] offset:45056
	s_waitcnt lgkmcnt(4)
	v_mfma_f32_16x16x32_bf16 v[46:49], v[164:167], v[184:187], v[46:49]
	s_waitcnt vmcnt(11)
	ds_write_b128 v190, v[240:243] offset:49168
	v_mfma_f32_16x16x32_bf16 v[42:45], v[168:171], v[184:187], v[42:45]
	s_waitcnt vmcnt(10)
	ds_write_b128 v190, v[244:247] offset:53264
	v_mfma_f32_16x16x32_bf16 v[38:41], v[172:175], v[184:187], v[38:41]
	s_waitcnt vmcnt(9)
	ds_write_b128 v190, v[248:251] offset:57360
	v_mfma_f32_16x16x32_bf16 v[34:37], v[176:179], v[184:187], v[34:37]
	s_waitcnt vmcnt(8)
	ds_write_b128 v190, v[252:255] offset:61456
	s_waitcnt lgkmcnt(0)
	s_barrier
	s_add_u32 s10, s10, 0x80
	s_addc_u32 s11, s11, 0
	s_add_u32 s28, s28, 0x80
	s_addc_u32 s29, s29, 0
	ds_read_b128 v[114:117], v188 offset:49168
	ds_read_b128 v[122:125], v188 offset:49680
	ds_read_b128 v[126:129], v188 offset:53264
	ds_read_b128 v[156:159], v188 offset:53776
	ds_read_b128 v[118:121], v112 offset:32768
	ds_read_b128 v[160:163], v112 offset:34816
	global_load_dwordx4 v[224:227], v216, s[10:11] offset:256
	global_load_dwordx4 v[228:231], v217, s[10:11] offset:256
	s_waitcnt lgkmcnt(1)
	v_mfma_f32_16x16x32_bf16 v[94:97], v[114:117], v[118:121], v[94:97]
	v_mfma_f32_16x16x32_bf16 v[90:93], v[122:125], v[118:121], v[90:93]
	global_load_dwordx4 v[232:235], v218, s[10:11] offset:256
	v_mfma_f32_16x16x32_bf16 v[86:89], v[126:129], v[118:121], v[86:89]
	v_mfma_f32_16x16x32_bf16 v[82:85], v[156:159], v[118:121], v[82:85]
	s_waitcnt lgkmcnt(0)
	v_mfma_f32_16x16x32_bf16 v[78:81], v[114:117], v[160:163], v[78:81]
	ds_read_b128 v[180:183], v112 offset:36864
	ds_read_b128 v[184:187], v112 offset:38912
	v_mfma_f32_16x16x32_bf16 v[74:77], v[122:125], v[160:163], v[74:77]
	v_mfma_f32_16x16x32_bf16 v[70:73], v[126:129], v[160:163], v[70:73]
	global_load_dwordx4 v[236:239], v219, s[10:11] offset:256
	v_mfma_f32_16x16x32_bf16 v[66:69], v[156:159], v[160:163], v[66:69]
	s_waitcnt lgkmcnt(1)
	v_mfma_f32_16x16x32_bf16 v[62:65], v[114:117], v[180:183], v[62:65]
	ds_read_b128 v[164:167], v189 offset:49168
	ds_read_b128 v[168:171], v189 offset:49680
	v_mfma_f32_16x16x32_bf16 v[58:61], v[122:125], v[180:183], v[58:61]
	global_load_dwordx4 v[240:243], v216, s[28:29] offset:256
	v_mfma_f32_16x16x32_bf16 v[54:57], v[126:129], v[180:183], v[54:57]
	ds_read_b128 v[172:175], v189 offset:53264
	ds_read_b128 v[176:179], v189 offset:53776
	v_mfma_f32_16x16x32_bf16 v[50:53], v[156:159], v[180:183], v[50:53]
	s_waitcnt lgkmcnt(4)
	v_mfma_f32_16x16x32_bf16 v[46:49], v[114:117], v[184:187], v[46:49]
	ds_read_b128 v[118:121], v113 offset:32768
	ds_read_b128 v[160:163], v113 offset:34816
	v_mfma_f32_16x16x32_bf16 v[42:45], v[122:125], v[184:187], v[42:45]
	v_mfma_f32_16x16x32_bf16 v[38:41], v[126:129], v[184:187], v[38:41]
	global_load_dwordx4 v[244:247], v217, s[28:29] offset:256
	v_mfma_f32_16x16x32_bf16 v[34:37], v[156:159], v[184:187], v[34:37]
	s_waitcnt lgkmcnt(1)
	v_mfma_f32_16x16x32_bf16 v[94:97], v[164:167], v[118:121], v[94:97]
	v_mfma_f32_16x16x32_bf16 v[90:93], v[168:171], v[118:121], v[90:93]
	global_load_dwordx4 v[248:251], v218, s[28:29] offset:256
	v_mfma_f32_16x16x32_bf16 v[86:89], v[172:175], v[118:121], v[86:89]
	v_mfma_f32_16x16x32_bf16 v[82:85], v[176:179], v[118:121], v[82:85]
	s_waitcnt lgkmcnt(0)
	v_mfma_f32_16x16x32_bf16 v[78:81], v[164:167], v[160:163], v[78:81]
	ds_read_b128 v[180:183], v113 offset:36864
	ds_read_b128 v[184:187], v113 offset:38912
	v_mfma_f32_16x16x32_bf16 v[74:77], v[168:171], v[160:163], v[74:77]
	v_mfma_f32_16x16x32_bf16 v[70:73], v[172:175], v[160:163], v[70:73]
	global_load_dwordx4 v[252:255], v219, s[28:29] offset:256
	v_mfma_f32_16x16x32_bf16 v[66:69], v[176:179], v[160:163], v[66:69]
	s_waitcnt lgkmcnt(1)
	v_mfma_f32_16x16x32_bf16 v[62:65], v[164:167], v[180:183], v[62:65]
	s_waitcnt vmcnt(15)
	ds_write_b128 v108, v[2:5]
	v_mfma_f32_16x16x32_bf16 v[58:61], v[168:171], v[180:183], v[58:61]
	s_waitcnt vmcnt(14)
	ds_write_b128 v108, v[6:9] offset:4096
	v_mfma_f32_16x16x32_bf16 v[54:57], v[172:175], v[180:183], v[54:57]
	s_waitcnt vmcnt(13)
	ds_write_b128 v108, v[10:13] offset:8192
	v_mfma_f32_16x16x32_bf16 v[50:53], v[176:179], v[180:183], v[50:53]
	s_waitcnt vmcnt(12)
	ds_write_b128 v108, v[14:17] offset:12288
	s_waitcnt lgkmcnt(4)
	v_mfma_f32_16x16x32_bf16 v[46:49], v[164:167], v[184:187], v[46:49]
	s_waitcnt vmcnt(11)
	ds_write_b128 v190, v[18:21] offset:16384
	v_mfma_f32_16x16x32_bf16 v[42:45], v[168:171], v[184:187], v[42:45]
	s_waitcnt vmcnt(10)
	ds_write_b128 v190, v[22:25] offset:20480
	v_mfma_f32_16x16x32_bf16 v[38:41], v[172:175], v[184:187], v[38:41]
	s_waitcnt vmcnt(9)
	ds_write_b128 v190, v[26:29] offset:24576
	v_mfma_f32_16x16x32_bf16 v[34:37], v[176:179], v[184:187], v[34:37]
	s_waitcnt vmcnt(8)
	ds_write_b128 v190, v[30:33] offset:28672
	s_waitcnt lgkmcnt(0)
	s_barrier
	s_add_u32 s10, s10, 0x80
	s_addc_u32 s11, s11, 0
	s_add_u32 s28, s28, 0x80
	s_addc_u32 s29, s29, 0
	s_sub_i32 vcc_lo, vcc_lo, 1
	s_cmp_lg_u32 vcc_lo, 0
	s_cbranch_scc1 .Lgq_o
	ds_read_b128 v[114:117], v188 offset:16384
	ds_read_b128 v[122:125], v188 offset:16896
	ds_read_b128 v[126:129], v188 offset:20480
	ds_read_b128 v[156:159], v188 offset:20992
	ds_read_b128 v[118:121], v112
	ds_read_b128 v[160:163], v112 offset:2048
	s_waitcnt lgkmcnt(1)
	v_mfma_f32_16x16x32_bf16 v[94:97], v[114:117], v[118:121], v[94:97]
	v_mfma_f32_16x16x32_bf16 v[90:93], v[122:125], v[118:121], v[90:93]
	v_mfma_f32_16x16x32_bf16 v[86:89], v[126:129], v[118:121], v[86:89]
	v_mfma_f32_16x16x32_bf16 v[82:85], v[156:159], v[118:121], v[82:85]
	s_waitcnt lgkmcnt(0)
	v_mfma_f32_16x16x32_bf16 v[78:81], v[114:117], v[160:163], v[78:81]
	ds_read_b128 v[180:183], v112 offset:4096
	ds_read_b128 v[184:187], v112 offset:6144
	v_mfma_f32_16x16x32_bf16 v[74:77], v[122:125], v[160:163], v[74:77]
	v_mfma_f32_16x16x32_bf16 v[70:73], v[126:129], v[160:163], v[70:73]
	v_mfma_f32_16x16x32_bf16 v[66:69], v[156:159], v[160:163], v[66:69]
	s_waitcnt lgkmcnt(1)
	v_mfma_f32_16x16x32_bf16 v[62:65], v[114:117], v[180:183], v[62:65]
	ds_read_b128 v[164:167], v189 offset:16384
	ds_read_b128 v[168:171], v189 offset:16896
	v_mfma_f32_16x16x32_bf16 v[58:61], v[122:125], v[180:183], v[58:61]
	v_mfma_f32_16x16x32_bf16 v[54:57], v[126:129], v[180:183], v[54:57]
	ds_read_b128 v[172:175], v189 offset:20480
	ds_read_b128 v[176:179], v189 offset:20992
	v_mfma_f32_16x16x32_bf16 v[50:53], v[156:159], v[180:183], v[50:53]
	s_waitcnt lgkmcnt(4)
	v_mfma_f32_16x16x32_bf16 v[46:49], v[114:117], v[184:187], v[46:49]
	ds_read_b128 v[118:121], v113
	ds_read_b128 v[160:163], v113 offset:2048
	v_mfma_f32_16x16x32_bf16 v[42:45], v[122:125], v[184:187], v[42:45]
	v_mfma_f32_16x16x32_bf16 v[38:41], v[126:129], v[184:187], v[38:41]
	v_mfma_f32_16x16x32_bf16 v[34:37], v[156:159], v[184:187], v[34:37]
	s_waitcnt lgkmcnt(1)
	v_mfma_f32_16x16x32_bf16 v[94:97], v[164:167], v[118:121], v[94:97]
	v_mfma_f32_16x16x32_bf16 v[90:93], v[168:171], v[118:121], v[90:93]
	v_mfma_f32_16x16x32_bf16 v[86:89], v[172:175], v[118:121], v[86:89]
	v_mfma_f32_16x16x32_bf16 v[82:85], v[176:179], v[118:121], v[82:85]
	s_waitcnt lgkmcnt(0)
	v_mfma_f32_16x16x32_bf16 v[78:81], v[164:167], v[160:163], v[78:81]
	ds_read_b128 v[180:183], v113 offset:4096
	ds_read_b128 v[184:187], v113 offset:6144
	v_mfma_f32_16x16x32_bf16 v[74:77], v[168:171], v[160:163], v[74:77]
	v_mfma_f32_16x16x32_bf16 v[70:73], v[172:175], v[160:163], v[70:73]
	v_mfma_f32_16x16x32_bf16 v[66:69], v[176:179], v[160:163], v[66:69]
	s_waitcnt lgkmcnt(1)
	v_mfma_f32_16x16x32_bf16 v[62:65], v[164:167], v[180:183], v[62:65]
	s_waitcnt vmcnt(7)
	ds_write_b128 v108, v[224:227] offset:32768
	v_mfma_f32_16x16x32_bf16 v[58:61], v[168:171], v[180:183], v[58:61]
	s_waitcnt vmcnt(6)
	ds_write_b128 v108, v[228:231] offset:36864
	v_mfma_f32_16x16x32_bf16 v[54:57], v[172:175], v[180:183], v[54:57]
	s_waitcnt vmcnt(5)
	ds_write_b128 v108, v[232:235] offset:40960
	v_mfma_f32_16x16x32_bf16 v[50:53], v[176:179], v[180:183], v[50:53]
	s_waitcnt vmcnt(4)
	ds_write_b128 v108, v[236:239] offset:45056
	s_waitcnt lgkmcnt(4)
	v_mfma_f32_16x16x32_bf16 v[46:49], v[164:167], v[184:187], v[46:49]
	s_waitcnt vmcnt(3)
	ds_write_b128 v190, v[240:243] offset:49168
	v_mfma_f32_16x16x32_bf16 v[42:45], v[168:171], v[184:187], v[42:45]
	s_waitcnt vmcnt(2)
	ds_write_b128 v190, v[244:247] offset:53264
	v_mfma_f32_16x16x32_bf16 v[38:41], v[172:175], v[184:187], v[38:41]
	s_waitcnt vmcnt(1)
	ds_write_b128 v190, v[248:251] offset:57360
	v_mfma_f32_16x16x32_bf16 v[34:37], v[176:179], v[184:187], v[34:37]
	s_waitcnt vmcnt(0)
	ds_write_b128 v190, v[252:255] offset:61456
	s_waitcnt lgkmcnt(0)
	s_barrier
	ds_read_b128 v[114:117], v188 offset:49168
	ds_read_b128 v[122:125], v188 offset:49680
	ds_read_b128 v[126:129], v188 offset:53264
	ds_read_b128 v[156:159], v188 offset:53776
	ds_read_b128 v[118:121], v112 offset:32768
	ds_read_b128 v[160:163], v112 offset:34816
	s_waitcnt lgkmcnt(1)
	v_mfma_f32_16x16x32_bf16 v[94:97], v[114:117], v[118:121], v[94:97]
	v_mfma_f32_16x16x32_bf16 v[90:93], v[122:125], v[118:121], v[90:93]
	v_mfma_f32_16x16x32_bf16 v[86:89], v[126:129], v[118:121], v[86:89]
	v_mfma_f32_16x16x32_bf16 v[82:85], v[156:159], v[118:121], v[82:85]
	s_waitcnt lgkmcnt(0)
	v_mfma_f32_16x16x32_bf16 v[78:81], v[114:117], v[160:163], v[78:81]
	ds_read_b128 v[180:183], v112 offset:36864
	ds_read_b128 v[184:187], v112 offset:38912
	v_mfma_f32_16x16x32_bf16 v[74:77], v[122:125], v[160:163], v[74:77]
	v_mfma_f32_16x16x32_bf16 v[70:73], v[126:129], v[160:163], v[70:73]
	v_mfma_f32_16x16x32_bf16 v[66:69], v[156:159], v[160:163], v[66:69]
	s_waitcnt lgkmcnt(1)
	v_mfma_f32_16x16x32_bf16 v[62:65], v[114:117], v[180:183], v[62:65]
	ds_read_b128 v[164:167], v189 offset:49168
	ds_read_b128 v[168:171], v189 offset:49680
	v_mfma_f32_16x16x32_bf16 v[58:61], v[122:125], v[180:183], v[58:61]
	v_mfma_f32_16x16x32_bf16 v[54:57], v[126:129], v[180:183], v[54:57]
	ds_read_b128 v[172:175], v189 offset:53264
	ds_read_b128 v[176:179], v189 offset:53776
	v_mfma_f32_16x16x32_bf16 v[50:53], v[156:159], v[180:183], v[50:53]
	s_waitcnt lgkmcnt(4)
	v_mfma_f32_16x16x32_bf16 v[46:49], v[114:117], v[184:187], v[46:49]
	ds_read_b128 v[118:121], v113 offset:32768
	ds_read_b128 v[160:163], v113 offset:34816
	v_mfma_f32_16x16x32_bf16 v[42:45], v[122:125], v[184:187], v[42:45]
	v_mfma_f32_16x16x32_bf16 v[38:41], v[126:129], v[184:187], v[38:41]
	v_mfma_f32_16x16x32_bf16 v[34:37], v[156:159], v[184:187], v[34:37]
	s_waitcnt lgkmcnt(1)
	v_mfma_f32_16x16x32_bf16 v[94:97], v[164:167], v[118:121], v[94:97]
	v_mfma_f32_16x16x32_bf16 v[90:93], v[168:171], v[118:121], v[90:93]
	v_mfma_f32_16x16x32_bf16 v[86:89], v[172:175], v[118:121], v[86:89]
	v_mfma_f32_16x16x32_bf16 v[82:85], v[176:179], v[118:121], v[82:85]
	s_waitcnt lgkmcnt(0)
	v_mfma_f32_16x16x32_bf16 v[78:81], v[164:167], v[160:163], v[78:81]
	ds_read_b128 v[180:183], v113 offset:36864
	ds_read_b128 v[184:187], v113 offset:38912
	v_mfma_f32_16x16x32_bf16 v[74:77], v[168:171], v[160:163], v[74:77]
	v_mfma_f32_16x16x32_bf16 v[70:73], v[172:175], v[160:163], v[70:73]
	v_mfma_f32_16x16x32_bf16 v[66:69], v[176:179], v[160:163], v[66:69]
	s_waitcnt lgkmcnt(1)
	v_mfma_f32_16x16x32_bf16 v[62:65], v[164:167], v[180:183], v[62:65]
	v_mfma_f32_16x16x32_bf16 v[58:61], v[168:171], v[180:183], v[58:61]
	v_mfma_f32_16x16x32_bf16 v[54:57], v[172:175], v[180:183], v[54:57]
	v_mfma_f32_16x16x32_bf16 v[50:53], v[176:179], v[180:183], v[50:53]
	s_waitcnt lgkmcnt(0)
	v_mfma_f32_16x16x32_bf16 v[46:49], v[164:167], v[184:187], v[46:49]
	v_mfma_f32_16x16x32_bf16 v[42:45], v[168:171], v[184:187], v[42:45]
	v_mfma_f32_16x16x32_bf16 v[38:41], v[172:175], v[184:187], v[38:41]
	v_mfma_f32_16x16x32_bf16 v[34:37], v[176:179], v[184:187], v[34:37]
	s_barrier
	s_branch .LBB0_1383
